# DMA staging rebalance (4/4/4/4 per segment) also in the FFN-down, W_out and W_in K loops
# baseline (speedup 1.0000x reference)
.LBB0_122:
	s_cmp_eq_u32 s89, 12
	s_cselect_b32 s42, s20, s65
	s_cselect_b32 s43, s16, s86
	s_cselect_b32 s45, s31, s88
	s_cselect_b32 s44, s59, s87
	s_add_u32 s38, s42, 0x80
	s_addc_u32 s39, s43, 0
	s_add_u32 s74, s44, 0x80
	s_addc_u32 s75, s45, 0
	s_add_i32 s35, 0, 0x10000
	s_mov_b64 s[18:19], s[68:69]
	v_add_u32_e32 v140, s35, v142
	s_add_i32 s49, 0, 0x14000
	ds_read_b128 v[136:139], v140
	ds_read_b128 v[144:147], v140 offset:1024
	ds_read_b128 v[148:151], v140 offset:2048
	ds_read_b128 v[152:155], v140 offset:3072
	v_add_u32_e32 v140, s49, v142
	ds_read_b128 v[156:159], v140
	ds_read_b128 v[160:163], v140 offset:1024
	ds_read_b128 v[164:167], v140 offset:2048
	ds_read_b128 v[168:171], v140 offset:3072
	s_mov_b32 m0, s81
	ds_read_b128 v[172:175], v143
	ds_read_b128 v[176:179], v143 offset:1024
	ds_read_b128 v[180:183], v143 offset:2048
	ds_read_b128 v[184:187], v143 offset:3072
	ds_read_b128 v[188:191], v143 offset:4096
	ds_read_b128 v[192:195], v143 offset:5120
	ds_read_b128 v[196:199], v143 offset:6144
	ds_read_b128 v[200:203], v143 offset:7168
	global_load_lds_dwordx4 v130, s[18:19]
	s_mov_b32 m0, s82
	s_nop 0
	global_load_lds_dwordx4 v132, s[18:19]
	s_add_u32 s18, s18, 0x40000
	s_addc_u32 s19, s19, 0
	s_add_i32 m0, s67, 0xc000
	s_nop 0
	global_load_lds_dwordx4 v130, s[18:19]
	s_add_i32 m0, s67, 0xe000
	s_nop 0
	global_load_lds_dwordx4 v132, s[18:19]
	s_waitcnt vmcnt(8)
	s_waitcnt lgkmcnt(0)
	s_barrier
	s_setprio 1
	s_waitcnt lgkmcnt(0)
	v_mfma_f32_16x16x32_bf16 v[126:129], v[136:139], v[172:175], v[126:129]
	v_mfma_f32_16x16x32_bf16 v[122:125], v[148:151], v[172:175], v[122:125]
	v_mfma_f32_16x16x32_bf16 v[110:113], v[136:139], v[180:183], v[110:113]
	v_mfma_f32_16x16x32_bf16 v[106:109], v[148:151], v[180:183], v[106:109]
	v_mfma_f32_16x16x32_bf16 v[92:95], v[136:139], v[188:191], v[92:95]
	v_mfma_f32_16x16x32_bf16 v[88:91], v[148:151], v[188:191], v[88:91]
	v_mfma_f32_16x16x32_bf16 v[76:79], v[136:139], v[196:199], v[76:79]
	v_mfma_f32_16x16x32_bf16 v[72:75], v[148:151], v[196:199], v[72:75]
	v_mfma_f32_16x16x32_bf16 v[126:129], v[144:147], v[176:179], v[126:129]
	v_mfma_f32_16x16x32_bf16 v[122:125], v[152:155], v[176:179], v[122:125]
	v_mfma_f32_16x16x32_bf16 v[110:113], v[144:147], v[184:187], v[110:113]
	v_mfma_f32_16x16x32_bf16 v[106:109], v[152:155], v[184:187], v[106:109]
	v_mfma_f32_16x16x32_bf16 v[92:95], v[144:147], v[192:195], v[92:95]
	v_mfma_f32_16x16x32_bf16 v[88:91], v[152:155], v[192:195], v[88:91]
	v_mfma_f32_16x16x32_bf16 v[76:79], v[144:147], v[200:203], v[76:79]
	v_mfma_f32_16x16x32_bf16 v[72:75], v[152:155], v[200:203], v[72:75]
	v_mfma_f32_16x16x32_bf16 v[118:121], v[156:159], v[172:175], v[118:121]
	v_mfma_f32_16x16x32_bf16 v[114:117], v[164:167], v[172:175], v[114:117]
	v_mfma_f32_16x16x32_bf16 v[102:105], v[156:159], v[180:183], v[102:105]
	v_mfma_f32_16x16x32_bf16 v[98:101], v[164:167], v[180:183], v[98:101]
	v_mfma_f32_16x16x32_bf16 v[84:87], v[156:159], v[188:191], v[84:87]
	v_mfma_f32_16x16x32_bf16 v[80:83], v[164:167], v[188:191], v[80:83]
	v_mfma_f32_16x16x32_bf16 v[68:71], v[156:159], v[196:199], v[68:71]
	v_mfma_f32_16x16x32_bf16 v[64:67], v[164:167], v[196:199], v[64:67]
	v_mfma_f32_16x16x32_bf16 v[118:121], v[160:163], v[176:179], v[118:121]
	v_mfma_f32_16x16x32_bf16 v[114:117], v[168:171], v[176:179], v[114:117]
	v_mfma_f32_16x16x32_bf16 v[102:105], v[160:163], v[184:187], v[102:105]
	v_mfma_f32_16x16x32_bf16 v[98:101], v[168:171], v[184:187], v[98:101]
	v_mfma_f32_16x16x32_bf16 v[84:87], v[160:163], v[192:195], v[84:87]
	v_mfma_f32_16x16x32_bf16 v[80:83], v[168:171], v[192:195], v[80:83]
	v_mfma_f32_16x16x32_bf16 v[68:71], v[160:163], v[200:203], v[68:71]
	v_mfma_f32_16x16x32_bf16 v[64:67], v[168:171], v[200:203], v[64:67]
	s_setprio 0
	s_barrier
	s_add_i32 s18, s35, s14
	s_mov_b32 m0, s18
	ds_read_b128 v[172:175], v143 offset:16384
	ds_read_b128 v[176:179], v143 offset:17408
	ds_read_b128 v[180:183], v143 offset:18432
	ds_read_b128 v[184:187], v143 offset:19456
	ds_read_b128 v[188:191], v143 offset:20480
	ds_read_b128 v[192:195], v143 offset:21504
	ds_read_b128 v[196:199], v143 offset:22528
	ds_read_b128 v[200:203], v143 offset:23552
	global_load_lds_dwordx4 v96, s[44:45]
	s_add_i32 m0, s18, 0x2000
	s_add_u32 s18, s44, 0x40000
	s_addc_u32 s19, s45, 0
	s_add_i32 s35, s49, s14
	global_load_lds_dwordx4 v134, s[44:45]
	s_mov_b32 m0, s35
	s_nop 0
	global_load_lds_dwordx4 v96, s[18:19]
	s_add_i32 m0, s35, 0x2000
	s_nop 0
	global_load_lds_dwordx4 v134, s[18:19]
	s_waitcnt vmcnt(6)
	s_waitcnt lgkmcnt(0)
	s_barrier
	s_setprio 1
	s_waitcnt lgkmcnt(0)
	v_mfma_f32_16x16x32_bf16 v[60:63], v[136:139], v[172:175], v[60:63]
	v_mfma_f32_16x16x32_bf16 v[56:59], v[148:151], v[172:175], v[56:59]
	v_mfma_f32_16x16x32_bf16 v[44:47], v[136:139], v[180:183], v[44:47]
	v_mfma_f32_16x16x32_bf16 v[40:43], v[148:151], v[180:183], v[40:43]
	v_mfma_f32_16x16x32_bf16 v[28:31], v[136:139], v[188:191], v[28:31]
	v_mfma_f32_16x16x32_bf16 v[24:27], v[148:151], v[188:191], v[24:27]
	v_mfma_f32_16x16x32_bf16 v[12:15], v[136:139], v[196:199], v[12:15]
	v_mfma_f32_16x16x32_bf16 v[8:11], v[148:151], v[196:199], v[8:11]
	v_mfma_f32_16x16x32_bf16 v[60:63], v[144:147], v[176:179], v[60:63]
	v_mfma_f32_16x16x32_bf16 v[56:59], v[152:155], v[176:179], v[56:59]
	v_mfma_f32_16x16x32_bf16 v[44:47], v[144:147], v[184:187], v[44:47]
	v_mfma_f32_16x16x32_bf16 v[40:43], v[152:155], v[184:187], v[40:43]
	v_mfma_f32_16x16x32_bf16 v[28:31], v[144:147], v[192:195], v[28:31]
	v_mfma_f32_16x16x32_bf16 v[24:27], v[152:155], v[192:195], v[24:27]
	v_mfma_f32_16x16x32_bf16 v[12:15], v[144:147], v[200:203], v[12:15]
	v_mfma_f32_16x16x32_bf16 v[8:11], v[152:155], v[200:203], v[8:11]
	v_mfma_f32_16x16x32_bf16 v[52:55], v[156:159], v[172:175], v[52:55]
	v_mfma_f32_16x16x32_bf16 v[48:51], v[164:167], v[172:175], v[48:51]
	v_mfma_f32_16x16x32_bf16 v[36:39], v[156:159], v[180:183], v[36:39]
	v_mfma_f32_16x16x32_bf16 v[32:35], v[164:167], v[180:183], v[32:35]
	v_mfma_f32_16x16x32_bf16 v[20:23], v[156:159], v[188:191], v[20:23]
	v_mfma_f32_16x16x32_bf16 v[16:19], v[164:167], v[188:191], v[16:19]
	v_mfma_f32_16x16x32_bf16 v[4:7], v[156:159], v[196:199], v[4:7]
	v_mfma_f32_16x16x32_bf16 v[0:3], v[164:167], v[196:199], v[0:3]
	v_mfma_f32_16x16x32_bf16 v[52:55], v[160:163], v[176:179], v[52:55]
	v_mfma_f32_16x16x32_bf16 v[48:51], v[168:171], v[176:179], v[48:51]
	v_mfma_f32_16x16x32_bf16 v[36:39], v[160:163], v[184:187], v[36:39]
	v_mfma_f32_16x16x32_bf16 v[32:35], v[168:171], v[184:187], v[32:35]
	v_mfma_f32_16x16x32_bf16 v[20:23], v[160:163], v[192:195], v[20:23]
	v_mfma_f32_16x16x32_bf16 v[16:19], v[168:171], v[192:195], v[16:19]
	v_mfma_f32_16x16x32_bf16 v[4:7], v[160:163], v[200:203], v[4:7]
	v_mfma_f32_16x16x32_bf16 v[0:3], v[168:171], v[200:203], v[0:3]
	s_setprio 0
	s_barrier
	s_add_i32 s35, 0, 0x18000
	v_add_u32_e32 v140, s35, v142
	s_add_i32 s44, 0, 0x1c000
	ds_read_b128 v[136:139], v140
	ds_read_b128 v[144:147], v140 offset:1024
	ds_read_b128 v[148:151], v140 offset:2048
	ds_read_b128 v[152:155], v140 offset:3072
	v_add_u32_e32 v140, s44, v142
	ds_read_b128 v[156:159], v140
	ds_read_b128 v[160:163], v140 offset:1024
	ds_read_b128 v[164:167], v140 offset:2048
	ds_read_b128 v[168:171], v140 offset:3072
	s_mov_b32 m0, s67
	s_nop 0
	global_load_lds_dwordx4 v130, s[42:43]
	s_mov_b32 m0, s73
	s_nop 0
	global_load_lds_dwordx4 v132, s[42:43]
	s_add_u32 s18, s42, 0x40000
	s_addc_u32 s19, s43, 0
	s_mov_b32 m0, s76
	ds_read_b128 v[172:175], v143 offset:32768
	ds_read_b128 v[176:179], v143 offset:33792
	ds_read_b128 v[180:183], v143 offset:34816
	ds_read_b128 v[184:187], v143 offset:35840
	ds_read_b128 v[188:191], v143 offset:36864
	ds_read_b128 v[192:195], v143 offset:37888
	ds_read_b128 v[196:199], v143 offset:38912
	ds_read_b128 v[200:203], v143 offset:39936
	global_load_lds_dwordx4 v130, s[18:19]
	s_mov_b32 m0, s77
	s_nop 0
	global_load_lds_dwordx4 v132, s[18:19]
	s_waitcnt vmcnt(8)
	s_waitcnt lgkmcnt(0)
	s_barrier
	s_setprio 1
	s_waitcnt lgkmcnt(0)
	v_mfma_f32_16x16x32_bf16 v[126:129], v[136:139], v[172:175], v[126:129]
	v_mfma_f32_16x16x32_bf16 v[122:125], v[148:151], v[172:175], v[122:125]
	v_mfma_f32_16x16x32_bf16 v[110:113], v[136:139], v[180:183], v[110:113]
	v_mfma_f32_16x16x32_bf16 v[106:109], v[148:151], v[180:183], v[106:109]
	v_mfma_f32_16x16x32_bf16 v[92:95], v[136:139], v[188:191], v[92:95]
	v_mfma_f32_16x16x32_bf16 v[88:91], v[148:151], v[188:191], v[88:91]
	v_mfma_f32_16x16x32_bf16 v[76:79], v[136:139], v[196:199], v[76:79]
	v_mfma_f32_16x16x32_bf16 v[72:75], v[148:151], v[196:199], v[72:75]
	v_mfma_f32_16x16x32_bf16 v[126:129], v[144:147], v[176:179], v[126:129]
	v_mfma_f32_16x16x32_bf16 v[122:125], v[152:155], v[176:179], v[122:125]
	v_mfma_f32_16x16x32_bf16 v[110:113], v[144:147], v[184:187], v[110:113]
	v_mfma_f32_16x16x32_bf16 v[106:109], v[152:155], v[184:187], v[106:109]
	v_mfma_f32_16x16x32_bf16 v[92:95], v[144:147], v[192:195], v[92:95]
	v_mfma_f32_16x16x32_bf16 v[88:91], v[152:155], v[192:195], v[88:91]
	v_mfma_f32_16x16x32_bf16 v[76:79], v[144:147], v[200:203], v[76:79]
	v_mfma_f32_16x16x32_bf16 v[72:75], v[152:155], v[200:203], v[72:75]
	v_mfma_f32_16x16x32_bf16 v[118:121], v[156:159], v[172:175], v[118:121]
	v_mfma_f32_16x16x32_bf16 v[114:117], v[164:167], v[172:175], v[114:117]
	v_mfma_f32_16x16x32_bf16 v[102:105], v[156:159], v[180:183], v[102:105]
	v_mfma_f32_16x16x32_bf16 v[98:101], v[164:167], v[180:183], v[98:101]
	v_mfma_f32_16x16x32_bf16 v[84:87], v[156:159], v[188:191], v[84:87]
	v_mfma_f32_16x16x32_bf16 v[80:83], v[164:167], v[188:191], v[80:83]
	v_mfma_f32_16x16x32_bf16 v[68:71], v[156:159], v[196:199], v[68:71]
	v_mfma_f32_16x16x32_bf16 v[64:67], v[164:167], v[196:199], v[64:67]
	v_mfma_f32_16x16x32_bf16 v[118:121], v[160:163], v[176:179], v[118:121]
	v_mfma_f32_16x16x32_bf16 v[114:117], v[168:171], v[176:179], v[114:117]
	v_mfma_f32_16x16x32_bf16 v[102:105], v[160:163], v[184:187], v[102:105]
	v_mfma_f32_16x16x32_bf16 v[98:101], v[168:171], v[184:187], v[98:101]
	v_mfma_f32_16x16x32_bf16 v[84:87], v[160:163], v[192:195], v[84:87]
	v_mfma_f32_16x16x32_bf16 v[80:83], v[168:171], v[192:195], v[80:83]
	v_mfma_f32_16x16x32_bf16 v[68:71], v[160:163], v[200:203], v[68:71]
	v_mfma_f32_16x16x32_bf16 v[64:67], v[168:171], v[200:203], v[64:67]
	s_setprio 0
	s_barrier
	s_add_i32 s18, s35, s14
	s_mov_b32 m0, s18
	ds_read_b128 v[172:175], v143 offset:49152
	ds_read_b128 v[176:179], v143 offset:50176
	ds_read_b128 v[180:183], v143 offset:51200
	ds_read_b128 v[184:187], v143 offset:52224
	ds_read_b128 v[188:191], v143 offset:53248
	ds_read_b128 v[192:195], v143 offset:54272
	ds_read_b128 v[196:199], v143 offset:55296
	ds_read_b128 v[200:203], v143 offset:56320
	global_load_lds_dwordx4 v96, s[74:75]
	s_add_i32 m0, s18, 0x2000
	s_add_u32 s18, s74, 0x40000
	s_addc_u32 s19, s75, 0
	s_add_i32 s35, s44, s14
	global_load_lds_dwordx4 v134, s[74:75]
	s_mov_b32 m0, s35
	s_nop 0
	global_load_lds_dwordx4 v96, s[18:19]
	s_add_i32 m0, s35, 0x2000
	s_nop 0
	global_load_lds_dwordx4 v134, s[18:19]
	s_waitcnt vmcnt(6)
	s_waitcnt lgkmcnt(0)
	s_barrier
	s_setprio 1
	s_waitcnt lgkmcnt(0)
	v_mfma_f32_16x16x32_bf16 v[60:63], v[136:139], v[172:175], v[60:63]
	v_mfma_f32_16x16x32_bf16 v[56:59], v[148:151], v[172:175], v[56:59]
	v_mfma_f32_16x16x32_bf16 v[44:47], v[136:139], v[180:183], v[44:47]
	v_mfma_f32_16x16x32_bf16 v[40:43], v[148:151], v[180:183], v[40:43]
	v_mfma_f32_16x16x32_bf16 v[28:31], v[136:139], v[188:191], v[28:31]
	v_mfma_f32_16x16x32_bf16 v[24:27], v[148:151], v[188:191], v[24:27]
	v_mfma_f32_16x16x32_bf16 v[12:15], v[136:139], v[196:199], v[12:15]
	v_mfma_f32_16x16x32_bf16 v[8:11], v[148:151], v[196:199], v[8:11]
	v_mfma_f32_16x16x32_bf16 v[60:63], v[144:147], v[176:179], v[60:63]
	v_mfma_f32_16x16x32_bf16 v[56:59], v[152:155], v[176:179], v[56:59]
	v_mfma_f32_16x16x32_bf16 v[44:47], v[144:147], v[184:187], v[44:47]
	v_mfma_f32_16x16x32_bf16 v[40:43], v[152:155], v[184:187], v[40:43]
	v_mfma_f32_16x16x32_bf16 v[28:31], v[144:147], v[192:195], v[28:31]
	v_mfma_f32_16x16x32_bf16 v[24:27], v[152:155], v[192:195], v[24:27]
	v_mfma_f32_16x16x32_bf16 v[12:15], v[144:147], v[200:203], v[12:15]
	v_mfma_f32_16x16x32_bf16 v[8:11], v[152:155], v[200:203], v[8:11]
	v_mfma_f32_16x16x32_bf16 v[52:55], v[156:159], v[172:175], v[52:55]
	v_mfma_f32_16x16x32_bf16 v[48:51], v[164:167], v[172:175], v[48:51]
	v_mfma_f32_16x16x32_bf16 v[36:39], v[156:159], v[180:183], v[36:39]
	v_mfma_f32_16x16x32_bf16 v[32:35], v[164:167], v[180:183], v[32:35]
	v_mfma_f32_16x16x32_bf16 v[20:23], v[156:159], v[188:191], v[20:23]
	v_mfma_f32_16x16x32_bf16 v[16:19], v[164:167], v[188:191], v[16:19]
	v_mfma_f32_16x16x32_bf16 v[4:7], v[156:159], v[196:199], v[4:7]
	v_mfma_f32_16x16x32_bf16 v[0:3], v[164:167], v[196:199], v[0:3]
	v_mfma_f32_16x16x32_bf16 v[52:55], v[160:163], v[176:179], v[52:55]
	v_mfma_f32_16x16x32_bf16 v[48:51], v[168:171], v[176:179], v[48:51]
	v_mfma_f32_16x16x32_bf16 v[36:39], v[160:163], v[184:187], v[36:39]
	v_mfma_f32_16x16x32_bf16 v[32:35], v[168:171], v[184:187], v[32:35]
	v_mfma_f32_16x16x32_bf16 v[20:23], v[160:163], v[192:195], v[20:23]
	v_mfma_f32_16x16x32_bf16 v[16:19], v[168:171], v[192:195], v[16:19]
	v_mfma_f32_16x16x32_bf16 v[4:7], v[160:163], v[200:203], v[4:7]
	v_mfma_f32_16x16x32_bf16 v[0:3], v[168:171], v[200:203], v[0:3]
	s_setprio 0
	s_barrier
	s_add_i32 s89, s89, 2
	s_add_u32 s65, s65, 0x100
	s_addc_u32 s86, s86, 0
	s_add_u32 s87, s87, 0x100
	s_addc_u32 s88, s88, 0
	s_add_u32 s68, s68, 0x100
	s_addc_u32 s69, s69, 0
	s_cmp_gt_u32 s89, 13
	s_cbranch_scc0 .LBB0_122
	s_and_b64 vcc, exec, s[28:29]
	s_cbranch_vccz .LBB0_125
	s_barrier

.LBB0_433:
	s_add_u32 s18, s10, 0x80
	s_addc_u32 s19, s11, 0
	s_add_u32 s10, s10, 0x100
	s_addc_u32 s11, s11, 0
	s_cmp_eq_u32 s92, 12
	s_cselect_b32 s42, s87, s10
	s_cselect_b32 s43, s9, s11
	s_cselect_b32 s45, s85, s94
	s_cselect_b32 s44, vcc_lo, vcc_hi
	s_add_u32 s38, s42, 0x80
	s_addc_u32 s39, s43, 0
	s_add_u32 s68, s44, 0x80
	s_addc_u32 s69, s45, 0
	s_add_i32 s35, 0, 0x10000
	s_add_i32 s49, 0, 0x14000
	v_add_u32_e32 v96, s35, v199
	v_add_u32_e32 v166, s49, v199
	ds_read_b128 v[138:141], v96
	ds_read_b128 v[142:145], v96 offset:1024
	ds_read_b128 v[146:149], v96 offset:2048
	ds_read_b128 v[150:153], v96 offset:3072
	s_waitcnt lgkmcnt(0)
	ds_read_b128 v[154:157], v166
	ds_read_b128 v[158:161], v166 offset:1024
	ds_read_b128 v[162:165], v166 offset:2048
	ds_read_b128 v[166:169], v166 offset:3072
	s_mov_b32 m0, s29
	ds_read_b128 v[170:173], v200
	ds_read_b128 v[174:177], v200 offset:1024
	ds_read_b128 v[178:181], v200 offset:2048
	ds_read_b128 v[182:185], v200 offset:3072
	ds_read_b128 v[190:193], v200 offset:4096
	ds_read_b128 v[194:197], v200 offset:5120
	ds_read_b128 v[202:205], v200 offset:6144
	ds_read_b128 v[206:209], v200 offset:7168
	global_load_lds_dwordx4 v130, s[18:19]
	s_mov_b32 m0, s16
	s_nop 0
	global_load_lds_dwordx4 v134, s[18:19]
	s_add_u32 s18, s18, 0x40000
	s_addc_u32 s19, s19, 0
	s_add_i32 m0, s73, 0xc000
	s_nop 0
	global_load_lds_dwordx4 v130, s[18:19]
	s_add_i32 m0, s73, 0xe000
	s_nop 0
	global_load_lds_dwordx4 v134, s[18:19]
	s_waitcnt vmcnt(8)
	s_waitcnt lgkmcnt(0)
	s_barrier
	s_setprio 1
	s_waitcnt lgkmcnt(0)
	v_mfma_f32_16x16x32_bf16 v[126:129], v[138:141], v[170:173], v[126:129]
	v_mfma_f32_16x16x32_bf16 v[122:125], v[146:149], v[170:173], v[122:125]
	v_mfma_f32_16x16x32_bf16 v[118:121], v[138:141], v[178:181], v[118:121]
	v_mfma_f32_16x16x32_bf16 v[110:113], v[146:149], v[178:181], v[110:113]
	v_mfma_f32_16x16x32_bf16 v[102:105], v[138:141], v[190:193], v[102:105]
	v_mfma_f32_16x16x32_bf16 v[92:95], v[146:149], v[190:193], v[92:95]
	v_mfma_f32_16x16x32_bf16 v[84:87], v[138:141], v[202:205], v[84:87]
	v_mfma_f32_16x16x32_bf16 v[76:79], v[146:149], v[202:205], v[76:79]
	v_mfma_f32_16x16x32_bf16 v[126:129], v[142:145], v[174:177], v[126:129]
	v_mfma_f32_16x16x32_bf16 v[122:125], v[150:153], v[174:177], v[122:125]
	v_mfma_f32_16x16x32_bf16 v[118:121], v[142:145], v[182:185], v[118:121]
	v_mfma_f32_16x16x32_bf16 v[110:113], v[150:153], v[182:185], v[110:113]
	v_mfma_f32_16x16x32_bf16 v[102:105], v[142:145], v[194:197], v[102:105]
	v_mfma_f32_16x16x32_bf16 v[92:95], v[150:153], v[194:197], v[92:95]
	v_mfma_f32_16x16x32_bf16 v[84:87], v[142:145], v[206:209], v[84:87]
	v_mfma_f32_16x16x32_bf16 v[76:79], v[150:153], v[206:209], v[76:79]
	v_mfma_f32_16x16x32_bf16 v[114:117], v[154:157], v[170:173], v[114:117]
	v_mfma_f32_16x16x32_bf16 v[106:109], v[162:165], v[170:173], v[106:109]
	v_mfma_f32_16x16x32_bf16 v[98:101], v[154:157], v[178:181], v[98:101]
	v_mfma_f32_16x16x32_bf16 v[88:91], v[162:165], v[178:181], v[88:91]
	v_mfma_f32_16x16x32_bf16 v[80:83], v[154:157], v[190:193], v[80:83]
	v_mfma_f32_16x16x32_bf16 v[72:75], v[162:165], v[190:193], v[72:75]
	v_mfma_f32_16x16x32_bf16 v[68:71], v[154:157], v[202:205], v[68:71]
	v_mfma_f32_16x16x32_bf16 v[64:67], v[162:165], v[202:205], v[64:67]
	v_mfma_f32_16x16x32_bf16 v[114:117], v[158:161], v[174:177], v[114:117]
	v_mfma_f32_16x16x32_bf16 v[106:109], v[166:169], v[174:177], v[106:109]
	v_mfma_f32_16x16x32_bf16 v[98:101], v[158:161], v[182:185], v[98:101]
	v_mfma_f32_16x16x32_bf16 v[88:91], v[166:169], v[182:185], v[88:91]
	v_mfma_f32_16x16x32_bf16 v[80:83], v[158:161], v[194:197], v[80:83]
	v_mfma_f32_16x16x32_bf16 v[72:75], v[166:169], v[194:197], v[72:75]
	v_mfma_f32_16x16x32_bf16 v[68:71], v[158:161], v[206:209], v[68:71]
	v_mfma_f32_16x16x32_bf16 v[64:67], v[166:169], v[206:209], v[64:67]
	s_setprio 0
	s_barrier
	s_add_i32 s18, s35, s72
	s_mov_b32 m0, s18
	ds_read_b128 v[170:173], v200 offset:16384
	ds_read_b128 v[174:177], v200 offset:17408
	ds_read_b128 v[178:181], v200 offset:18432
	ds_read_b128 v[182:185], v200 offset:19456
	ds_read_b128 v[190:193], v200 offset:20480
	ds_read_b128 v[194:197], v200 offset:21504
	ds_read_b128 v[202:205], v200 offset:22528
	ds_read_b128 v[206:209], v200 offset:23552
	global_load_lds_dwordx4 v132, s[44:45]
	s_add_i32 m0, s18, 0x2000
	s_add_u32 s18, s44, 0x40000
	s_addc_u32 s19, s45, 0
	s_add_i32 s35, s49, s72
	global_load_lds_dwordx4 v136, s[44:45]
	s_mov_b32 m0, s35
	s_nop 0
	global_load_lds_dwordx4 v132, s[18:19]
	s_add_i32 m0, s35, 0x2000
	s_nop 0
	global_load_lds_dwordx4 v136, s[18:19]
	s_waitcnt vmcnt(6)
	s_waitcnt lgkmcnt(0)
	s_barrier
	s_setprio 1
	s_waitcnt lgkmcnt(0)
	v_mfma_f32_16x16x32_bf16 v[60:63], v[138:141], v[170:173], v[60:63]
	v_mfma_f32_16x16x32_bf16 v[56:59], v[146:149], v[170:173], v[56:59]
	v_mfma_f32_16x16x32_bf16 v[52:55], v[138:141], v[178:181], v[52:55]
	v_mfma_f32_16x16x32_bf16 v[44:47], v[146:149], v[178:181], v[44:47]
	v_mfma_f32_16x16x32_bf16 v[36:39], v[138:141], v[190:193], v[36:39]
	v_mfma_f32_16x16x32_bf16 v[28:31], v[146:149], v[190:193], v[28:31]
	v_mfma_f32_16x16x32_bf16 v[20:23], v[138:141], v[202:205], v[20:23]
	v_mfma_f32_16x16x32_bf16 v[12:15], v[146:149], v[202:205], v[12:15]
	v_mfma_f32_16x16x32_bf16 v[60:63], v[142:145], v[174:177], v[60:63]
	v_mfma_f32_16x16x32_bf16 v[56:59], v[150:153], v[174:177], v[56:59]
	v_mfma_f32_16x16x32_bf16 v[52:55], v[142:145], v[182:185], v[52:55]
	v_mfma_f32_16x16x32_bf16 v[44:47], v[150:153], v[182:185], v[44:47]
	v_mfma_f32_16x16x32_bf16 v[36:39], v[142:145], v[194:197], v[36:39]
	v_mfma_f32_16x16x32_bf16 v[28:31], v[150:153], v[194:197], v[28:31]
	v_mfma_f32_16x16x32_bf16 v[20:23], v[142:145], v[206:209], v[20:23]
	v_mfma_f32_16x16x32_bf16 v[12:15], v[150:153], v[206:209], v[12:15]
	v_mfma_f32_16x16x32_bf16 v[48:51], v[154:157], v[170:173], v[48:51]
	v_mfma_f32_16x16x32_bf16 v[40:43], v[162:165], v[170:173], v[40:43]
	v_mfma_f32_16x16x32_bf16 v[32:35], v[154:157], v[178:181], v[32:35]
	v_mfma_f32_16x16x32_bf16 v[24:27], v[162:165], v[178:181], v[24:27]
	v_mfma_f32_16x16x32_bf16 v[16:19], v[154:157], v[190:193], v[16:19]
	v_mfma_f32_16x16x32_bf16 v[8:11], v[162:165], v[190:193], v[8:11]
	v_mfma_f32_16x16x32_bf16 v[4:7], v[154:157], v[202:205], v[4:7]
	v_mfma_f32_16x16x32_bf16 v[0:3], v[162:165], v[202:205], v[0:3]
	v_mfma_f32_16x16x32_bf16 v[48:51], v[158:161], v[174:177], v[48:51]
	v_mfma_f32_16x16x32_bf16 v[40:43], v[166:169], v[174:177], v[40:43]
	v_mfma_f32_16x16x32_bf16 v[32:35], v[158:161], v[182:185], v[32:35]
	v_mfma_f32_16x16x32_bf16 v[24:27], v[166:169], v[182:185], v[24:27]
	v_mfma_f32_16x16x32_bf16 v[16:19], v[158:161], v[194:197], v[16:19]
	v_mfma_f32_16x16x32_bf16 v[8:11], v[166:169], v[194:197], v[8:11]
	v_mfma_f32_16x16x32_bf16 v[4:7], v[158:161], v[206:209], v[4:7]
	v_mfma_f32_16x16x32_bf16 v[0:3], v[166:169], v[206:209], v[0:3]
	s_setprio 0
	s_barrier
	s_add_i32 s35, 0, 0x18000
	v_add_u32_e32 v96, s35, v199
	s_add_i32 s44, 0, 0x1c000
	ds_read_b128 v[138:141], v96
	ds_read_b128 v[142:145], v96 offset:1024
	ds_read_b128 v[146:149], v96 offset:2048
	ds_read_b128 v[150:153], v96 offset:3072
	v_add_u32_e32 v96, s44, v199
	ds_read_b128 v[154:157], v96
	ds_read_b128 v[158:161], v96 offset:1024
	ds_read_b128 v[162:165], v96 offset:2048
	ds_read_b128 v[166:169], v96 offset:3072
	s_mov_b32 m0, s73
	s_nop 0
	global_load_lds_dwordx4 v130, s[42:43]
	s_mov_b32 m0, s74
	s_nop 0
	global_load_lds_dwordx4 v134, s[42:43]
	s_add_u32 s18, s42, 0x40000
	s_addc_u32 s19, s43, 0
	s_mov_b32 m0, s75
	ds_read_b128 v[170:173], v200 offset:32768
	ds_read_b128 v[174:177], v200 offset:33792
	ds_read_b128 v[178:181], v200 offset:34816
	ds_read_b128 v[182:185], v200 offset:35840
	ds_read_b128 v[190:193], v200 offset:36864
	ds_read_b128 v[194:197], v200 offset:37888
	ds_read_b128 v[202:205], v200 offset:38912
	ds_read_b128 v[206:209], v200 offset:39936
	global_load_lds_dwordx4 v130, s[18:19]
	s_mov_b32 m0, s83
	s_nop 0
	global_load_lds_dwordx4 v134, s[18:19]
	s_waitcnt vmcnt(8)
	s_waitcnt lgkmcnt(0)
	s_barrier
	s_setprio 1
	s_waitcnt lgkmcnt(0)
	v_mfma_f32_16x16x32_bf16 v[126:129], v[138:141], v[170:173], v[126:129]
	v_mfma_f32_16x16x32_bf16 v[122:125], v[146:149], v[170:173], v[122:125]
	v_mfma_f32_16x16x32_bf16 v[118:121], v[138:141], v[178:181], v[118:121]
	v_mfma_f32_16x16x32_bf16 v[110:113], v[146:149], v[178:181], v[110:113]
	v_mfma_f32_16x16x32_bf16 v[102:105], v[138:141], v[190:193], v[102:105]
	v_mfma_f32_16x16x32_bf16 v[92:95], v[146:149], v[190:193], v[92:95]
	v_mfma_f32_16x16x32_bf16 v[84:87], v[138:141], v[202:205], v[84:87]
	v_mfma_f32_16x16x32_bf16 v[76:79], v[146:149], v[202:205], v[76:79]
	v_mfma_f32_16x16x32_bf16 v[126:129], v[142:145], v[174:177], v[126:129]
	v_mfma_f32_16x16x32_bf16 v[122:125], v[150:153], v[174:177], v[122:125]
	v_mfma_f32_16x16x32_bf16 v[118:121], v[142:145], v[182:185], v[118:121]
	v_mfma_f32_16x16x32_bf16 v[110:113], v[150:153], v[182:185], v[110:113]
	v_mfma_f32_16x16x32_bf16 v[102:105], v[142:145], v[194:197], v[102:105]
	v_mfma_f32_16x16x32_bf16 v[92:95], v[150:153], v[194:197], v[92:95]
	v_mfma_f32_16x16x32_bf16 v[84:87], v[142:145], v[206:209], v[84:87]
	v_mfma_f32_16x16x32_bf16 v[76:79], v[150:153], v[206:209], v[76:79]
	v_mfma_f32_16x16x32_bf16 v[114:117], v[154:157], v[170:173], v[114:117]
	v_mfma_f32_16x16x32_bf16 v[106:109], v[162:165], v[170:173], v[106:109]
	v_mfma_f32_16x16x32_bf16 v[98:101], v[154:157], v[178:181], v[98:101]
	v_mfma_f32_16x16x32_bf16 v[88:91], v[162:165], v[178:181], v[88:91]
	v_mfma_f32_16x16x32_bf16 v[80:83], v[154:157], v[190:193], v[80:83]
	v_mfma_f32_16x16x32_bf16 v[72:75], v[162:165], v[190:193], v[72:75]
	v_mfma_f32_16x16x32_bf16 v[68:71], v[154:157], v[202:205], v[68:71]
	v_mfma_f32_16x16x32_bf16 v[64:67], v[162:165], v[202:205], v[64:67]
	v_mfma_f32_16x16x32_bf16 v[114:117], v[158:161], v[174:177], v[114:117]
	v_mfma_f32_16x16x32_bf16 v[106:109], v[166:169], v[174:177], v[106:109]
	v_mfma_f32_16x16x32_bf16 v[98:101], v[158:161], v[182:185], v[98:101]
	v_mfma_f32_16x16x32_bf16 v[88:91], v[166:169], v[182:185], v[88:91]
	v_mfma_f32_16x16x32_bf16 v[80:83], v[158:161], v[194:197], v[80:83]
	v_mfma_f32_16x16x32_bf16 v[72:75], v[166:169], v[194:197], v[72:75]
	v_mfma_f32_16x16x32_bf16 v[68:71], v[158:161], v[206:209], v[68:71]
	v_mfma_f32_16x16x32_bf16 v[64:67], v[166:169], v[206:209], v[64:67]
	s_setprio 0
	s_barrier
	s_add_i32 s18, s35, s72
	s_mov_b32 m0, s18
	ds_read_b128 v[170:173], v200 offset:49152
	ds_read_b128 v[174:177], v200 offset:50176
	ds_read_b128 v[178:181], v200 offset:51200
	ds_read_b128 v[182:185], v200 offset:52224
	ds_read_b128 v[190:193], v200 offset:53248
	ds_read_b128 v[194:197], v200 offset:54272
	ds_read_b128 v[202:205], v200 offset:55296
	ds_read_b128 v[206:209], v200 offset:56320
	global_load_lds_dwordx4 v132, s[68:69]
	s_add_i32 m0, s18, 0x2000
	s_add_u32 s18, s68, 0x40000
	s_addc_u32 s19, s69, 0
	s_add_i32 s35, s44, s72
	global_load_lds_dwordx4 v136, s[68:69]
	s_mov_b32 m0, s35
	s_nop 0
	global_load_lds_dwordx4 v132, s[18:19]
	s_add_i32 m0, s35, 0x2000
	s_nop 0
	global_load_lds_dwordx4 v136, s[18:19]
	s_waitcnt vmcnt(6)
	s_waitcnt lgkmcnt(0)
	s_barrier
	s_setprio 1
	s_waitcnt lgkmcnt(0)
	v_mfma_f32_16x16x32_bf16 v[60:63], v[138:141], v[170:173], v[60:63]
	v_mfma_f32_16x16x32_bf16 v[56:59], v[146:149], v[170:173], v[56:59]
	v_mfma_f32_16x16x32_bf16 v[52:55], v[138:141], v[178:181], v[52:55]
	v_mfma_f32_16x16x32_bf16 v[44:47], v[146:149], v[178:181], v[44:47]
	v_mfma_f32_16x16x32_bf16 v[36:39], v[138:141], v[190:193], v[36:39]
	v_mfma_f32_16x16x32_bf16 v[28:31], v[146:149], v[190:193], v[28:31]
	v_mfma_f32_16x16x32_bf16 v[20:23], v[138:141], v[202:205], v[20:23]
	v_mfma_f32_16x16x32_bf16 v[12:15], v[146:149], v[202:205], v[12:15]
	v_mfma_f32_16x16x32_bf16 v[60:63], v[142:145], v[174:177], v[60:63]
	v_mfma_f32_16x16x32_bf16 v[56:59], v[150:153], v[174:177], v[56:59]
	v_mfma_f32_16x16x32_bf16 v[52:55], v[142:145], v[182:185], v[52:55]
	v_mfma_f32_16x16x32_bf16 v[44:47], v[150:153], v[182:185], v[44:47]
	v_mfma_f32_16x16x32_bf16 v[36:39], v[142:145], v[194:197], v[36:39]
	v_mfma_f32_16x16x32_bf16 v[28:31], v[150:153], v[194:197], v[28:31]
	v_mfma_f32_16x16x32_bf16 v[20:23], v[142:145], v[206:209], v[20:23]
	v_mfma_f32_16x16x32_bf16 v[12:15], v[150:153], v[206:209], v[12:15]
	v_mfma_f32_16x16x32_bf16 v[48:51], v[154:157], v[170:173], v[48:51]
	v_mfma_f32_16x16x32_bf16 v[40:43], v[162:165], v[170:173], v[40:43]
	v_mfma_f32_16x16x32_bf16 v[32:35], v[154:157], v[178:181], v[32:35]
	v_mfma_f32_16x16x32_bf16 v[24:27], v[162:165], v[178:181], v[24:27]
	v_mfma_f32_16x16x32_bf16 v[16:19], v[154:157], v[190:193], v[16:19]
	v_mfma_f32_16x16x32_bf16 v[8:11], v[162:165], v[190:193], v[8:11]
	v_mfma_f32_16x16x32_bf16 v[4:7], v[154:157], v[202:205], v[4:7]
	v_mfma_f32_16x16x32_bf16 v[0:3], v[162:165], v[202:205], v[0:3]
	v_mfma_f32_16x16x32_bf16 v[48:51], v[158:161], v[174:177], v[48:51]
	v_mfma_f32_16x16x32_bf16 v[40:43], v[166:169], v[174:177], v[40:43]
	v_mfma_f32_16x16x32_bf16 v[32:35], v[158:161], v[182:185], v[32:35]
	v_mfma_f32_16x16x32_bf16 v[24:27], v[166:169], v[182:185], v[24:27]
	v_mfma_f32_16x16x32_bf16 v[16:19], v[158:161], v[194:197], v[16:19]
	v_mfma_f32_16x16x32_bf16 v[8:11], v[166:169], v[194:197], v[8:11]
	v_mfma_f32_16x16x32_bf16 v[4:7], v[158:161], v[206:209], v[4:7]
	v_mfma_f32_16x16x32_bf16 v[0:3], v[166:169], v[206:209], v[0:3]
	s_setprio 0
	s_barrier
	s_add_i32 s92, s92, 2
	s_add_u32 vcc_hi, vcc_hi, 0x100
	s_addc_u32 s94, s94, 0
	s_cmp_gt_u32 s92, 13
	s_cbranch_scc0 .LBB0_433
	s_and_b64 vcc, exec, s[76:77]
	s_cbranch_vccz .LBB0_436
	s_barrier

.LBB0_703:
	s_cmp_eq_u32 s85, 40
	s_cselect_b32 s42, s8, s81
	s_cselect_b32 s43, s9, s82
	s_cselect_b32 s45, s59, s84
	s_cselect_b32 s44, s58, s83
	s_add_u32 s38, s42, 0x80
	s_addc_u32 s39, s43, 0
	s_add_u32 s62, s44, 0x80
	s_addc_u32 s63, s45, 0
	s_add_i32 s35, 0, 0x10000
	s_mov_b64 s[18:19], s[60:61]
	v_add_u32_e32 v140, s35, v142
	s_add_i32 s49, 0, 0x14000
	ds_read_b128 v[136:139], v140
	ds_read_b128 v[144:147], v140 offset:1024
	ds_read_b128 v[148:151], v140 offset:2048
	ds_read_b128 v[152:155], v140 offset:3072
	v_add_u32_e32 v140, s49, v142
	ds_read_b128 v[156:159], v140
	ds_read_b128 v[160:163], v140 offset:1024
	ds_read_b128 v[164:167], v140 offset:2048
	ds_read_b128 v[168:171], v140 offset:3072
	s_mov_b32 m0, s74
	ds_read_b128 v[172:175], v143
	ds_read_b128 v[176:179], v143 offset:1024
	ds_read_b128 v[180:183], v143 offset:2048
	ds_read_b128 v[190:193], v143 offset:3072
	ds_read_b128 v[194:197], v143 offset:4096
	ds_read_b128 v[198:201], v143 offset:5120
	ds_read_b128 v[202:205], v143 offset:6144
	ds_read_b128 v[206:209], v143 offset:7168
	global_load_lds_dwordx4 v130, s[18:19]
	s_mov_b32 m0, s75
	s_nop 0
	global_load_lds_dwordx4 v132, s[18:19]
	s_add_u32 s18, s18, 0xb0000
	s_addc_u32 s19, s19, 0
	s_add_i32 m0, s66, 0xc000
	s_nop 0
	global_load_lds_dwordx4 v130, s[18:19]
	s_add_i32 m0, s66, 0xe000
	s_nop 0
	global_load_lds_dwordx4 v132, s[18:19]
	s_waitcnt vmcnt(8)
	s_waitcnt lgkmcnt(0)
	s_barrier
	s_setprio 1
	s_waitcnt lgkmcnt(0)
	v_mfma_f32_16x16x32_bf16 v[126:129], v[136:139], v[172:175], v[126:129]
	v_mfma_f32_16x16x32_bf16 v[122:125], v[148:151], v[172:175], v[122:125]
	v_mfma_f32_16x16x32_bf16 v[110:113], v[136:139], v[180:183], v[110:113]
	v_mfma_f32_16x16x32_bf16 v[106:109], v[148:151], v[180:183], v[106:109]
	v_mfma_f32_16x16x32_bf16 v[92:95], v[136:139], v[194:197], v[92:95]
	v_mfma_f32_16x16x32_bf16 v[88:91], v[148:151], v[194:197], v[88:91]
	v_mfma_f32_16x16x32_bf16 v[76:79], v[136:139], v[202:205], v[76:79]
	v_mfma_f32_16x16x32_bf16 v[72:75], v[148:151], v[202:205], v[72:75]
	v_mfma_f32_16x16x32_bf16 v[126:129], v[144:147], v[176:179], v[126:129]
	v_mfma_f32_16x16x32_bf16 v[122:125], v[152:155], v[176:179], v[122:125]
	v_mfma_f32_16x16x32_bf16 v[110:113], v[144:147], v[190:193], v[110:113]
	v_mfma_f32_16x16x32_bf16 v[106:109], v[152:155], v[190:193], v[106:109]
	v_mfma_f32_16x16x32_bf16 v[92:95], v[144:147], v[198:201], v[92:95]
	v_mfma_f32_16x16x32_bf16 v[88:91], v[152:155], v[198:201], v[88:91]
	v_mfma_f32_16x16x32_bf16 v[76:79], v[144:147], v[206:209], v[76:79]
	v_mfma_f32_16x16x32_bf16 v[72:75], v[152:155], v[206:209], v[72:75]
	v_mfma_f32_16x16x32_bf16 v[118:121], v[156:159], v[172:175], v[118:121]
	v_mfma_f32_16x16x32_bf16 v[114:117], v[164:167], v[172:175], v[114:117]
	v_mfma_f32_16x16x32_bf16 v[102:105], v[156:159], v[180:183], v[102:105]
	v_mfma_f32_16x16x32_bf16 v[98:101], v[164:167], v[180:183], v[98:101]
	v_mfma_f32_16x16x32_bf16 v[84:87], v[156:159], v[194:197], v[84:87]
	v_mfma_f32_16x16x32_bf16 v[80:83], v[164:167], v[194:197], v[80:83]
	v_mfma_f32_16x16x32_bf16 v[68:71], v[156:159], v[202:205], v[68:71]
	v_mfma_f32_16x16x32_bf16 v[64:67], v[164:167], v[202:205], v[64:67]
	v_mfma_f32_16x16x32_bf16 v[118:121], v[160:163], v[176:179], v[118:121]
	v_mfma_f32_16x16x32_bf16 v[114:117], v[168:171], v[176:179], v[114:117]
	v_mfma_f32_16x16x32_bf16 v[102:105], v[160:163], v[190:193], v[102:105]
	v_mfma_f32_16x16x32_bf16 v[98:101], v[168:171], v[190:193], v[98:101]
	v_mfma_f32_16x16x32_bf16 v[84:87], v[160:163], v[198:201], v[84:87]
	v_mfma_f32_16x16x32_bf16 v[80:83], v[168:171], v[198:201], v[80:83]
	v_mfma_f32_16x16x32_bf16 v[68:71], v[160:163], v[206:209], v[68:71]
	v_mfma_f32_16x16x32_bf16 v[64:67], v[168:171], v[206:209], v[64:67]
	s_setprio 0
	s_barrier
	s_add_i32 s18, s35, s14
	s_mov_b32 m0, s18
	ds_read_b128 v[172:175], v143 offset:16384
	ds_read_b128 v[176:179], v143 offset:17408
	ds_read_b128 v[180:183], v143 offset:18432
	ds_read_b128 v[190:193], v143 offset:19456
	ds_read_b128 v[194:197], v143 offset:20480
	ds_read_b128 v[198:201], v143 offset:21504
	ds_read_b128 v[202:205], v143 offset:22528
	ds_read_b128 v[206:209], v143 offset:23552
	global_load_lds_dwordx4 v96, s[44:45]
	s_add_i32 m0, s18, 0x2000
	s_add_u32 s18, s44, 0xb0000
	s_addc_u32 s19, s45, 0
	s_add_i32 s35, s49, s14
	global_load_lds_dwordx4 v134, s[44:45]
	s_mov_b32 m0, s35
	s_nop 0
	global_load_lds_dwordx4 v96, s[18:19]
	s_add_i32 m0, s35, 0x2000
	s_nop 0
	global_load_lds_dwordx4 v134, s[18:19]
	s_waitcnt vmcnt(6)
	s_waitcnt lgkmcnt(0)
	s_barrier
	s_setprio 1
	s_waitcnt lgkmcnt(0)
	v_mfma_f32_16x16x32_bf16 v[60:63], v[136:139], v[172:175], v[60:63]
	v_mfma_f32_16x16x32_bf16 v[56:59], v[148:151], v[172:175], v[56:59]
	v_mfma_f32_16x16x32_bf16 v[44:47], v[136:139], v[180:183], v[44:47]
	v_mfma_f32_16x16x32_bf16 v[40:43], v[148:151], v[180:183], v[40:43]
	v_mfma_f32_16x16x32_bf16 v[28:31], v[136:139], v[194:197], v[28:31]
	v_mfma_f32_16x16x32_bf16 v[24:27], v[148:151], v[194:197], v[24:27]
	v_mfma_f32_16x16x32_bf16 v[12:15], v[136:139], v[202:205], v[12:15]
	v_mfma_f32_16x16x32_bf16 v[8:11], v[148:151], v[202:205], v[8:11]
	v_mfma_f32_16x16x32_bf16 v[60:63], v[144:147], v[176:179], v[60:63]
	v_mfma_f32_16x16x32_bf16 v[56:59], v[152:155], v[176:179], v[56:59]
	v_mfma_f32_16x16x32_bf16 v[44:47], v[144:147], v[190:193], v[44:47]
	v_mfma_f32_16x16x32_bf16 v[40:43], v[152:155], v[190:193], v[40:43]
	v_mfma_f32_16x16x32_bf16 v[28:31], v[144:147], v[198:201], v[28:31]
	v_mfma_f32_16x16x32_bf16 v[24:27], v[152:155], v[198:201], v[24:27]
	v_mfma_f32_16x16x32_bf16 v[12:15], v[144:147], v[206:209], v[12:15]
	v_mfma_f32_16x16x32_bf16 v[8:11], v[152:155], v[206:209], v[8:11]
	v_mfma_f32_16x16x32_bf16 v[52:55], v[156:159], v[172:175], v[52:55]
	v_mfma_f32_16x16x32_bf16 v[48:51], v[164:167], v[172:175], v[48:51]
	v_mfma_f32_16x16x32_bf16 v[36:39], v[156:159], v[180:183], v[36:39]
	v_mfma_f32_16x16x32_bf16 v[32:35], v[164:167], v[180:183], v[32:35]
	v_mfma_f32_16x16x32_bf16 v[20:23], v[156:159], v[194:197], v[20:23]
	v_mfma_f32_16x16x32_bf16 v[16:19], v[164:167], v[194:197], v[16:19]
	v_mfma_f32_16x16x32_bf16 v[4:7], v[156:159], v[202:205], v[4:7]
	v_mfma_f32_16x16x32_bf16 v[0:3], v[164:167], v[202:205], v[0:3]
	v_mfma_f32_16x16x32_bf16 v[52:55], v[160:163], v[176:179], v[52:55]
	v_mfma_f32_16x16x32_bf16 v[48:51], v[168:171], v[176:179], v[48:51]
	v_mfma_f32_16x16x32_bf16 v[36:39], v[160:163], v[190:193], v[36:39]
	v_mfma_f32_16x16x32_bf16 v[32:35], v[168:171], v[190:193], v[32:35]
	v_mfma_f32_16x16x32_bf16 v[20:23], v[160:163], v[198:201], v[20:23]
	v_mfma_f32_16x16x32_bf16 v[16:19], v[168:171], v[198:201], v[16:19]
	v_mfma_f32_16x16x32_bf16 v[4:7], v[160:163], v[206:209], v[4:7]
	v_mfma_f32_16x16x32_bf16 v[0:3], v[168:171], v[206:209], v[0:3]
	s_setprio 0
	s_barrier
	s_add_i32 s35, 0, 0x18000
	v_add_u32_e32 v140, s35, v142
	s_add_i32 s44, 0, 0x1c000
	ds_read_b128 v[136:139], v140
	ds_read_b128 v[144:147], v140 offset:1024
	ds_read_b128 v[148:151], v140 offset:2048
	ds_read_b128 v[152:155], v140 offset:3072
	v_add_u32_e32 v140, s44, v142
	ds_read_b128 v[156:159], v140
	ds_read_b128 v[160:163], v140 offset:1024
	ds_read_b128 v[164:167], v140 offset:2048
	ds_read_b128 v[168:171], v140 offset:3072
	s_mov_b32 m0, s66
	s_nop 0
	global_load_lds_dwordx4 v130, s[42:43]
	s_mov_b32 m0, s67
	s_nop 0
	global_load_lds_dwordx4 v132, s[42:43]
	s_add_u32 s18, s42, 0xb0000
	s_addc_u32 s19, s43, 0
	s_mov_b32 m0, s68
	ds_read_b128 v[172:175], v143 offset:32768
	ds_read_b128 v[176:179], v143 offset:33792
	ds_read_b128 v[180:183], v143 offset:34816
	ds_read_b128 v[190:193], v143 offset:35840
	ds_read_b128 v[194:197], v143 offset:36864
	ds_read_b128 v[198:201], v143 offset:37888
	ds_read_b128 v[202:205], v143 offset:38912
	ds_read_b128 v[206:209], v143 offset:39936
	global_load_lds_dwordx4 v130, s[18:19]
	s_mov_b32 m0, s69
	s_nop 0
	global_load_lds_dwordx4 v132, s[18:19]
	s_waitcnt vmcnt(8)
	s_waitcnt lgkmcnt(0)
	s_barrier
	s_setprio 1
	s_waitcnt lgkmcnt(0)
	v_mfma_f32_16x16x32_bf16 v[126:129], v[136:139], v[172:175], v[126:129]
	v_mfma_f32_16x16x32_bf16 v[122:125], v[148:151], v[172:175], v[122:125]
	v_mfma_f32_16x16x32_bf16 v[110:113], v[136:139], v[180:183], v[110:113]
	v_mfma_f32_16x16x32_bf16 v[106:109], v[148:151], v[180:183], v[106:109]
	v_mfma_f32_16x16x32_bf16 v[92:95], v[136:139], v[194:197], v[92:95]
	v_mfma_f32_16x16x32_bf16 v[88:91], v[148:151], v[194:197], v[88:91]
	v_mfma_f32_16x16x32_bf16 v[76:79], v[136:139], v[202:205], v[76:79]
	v_mfma_f32_16x16x32_bf16 v[72:75], v[148:151], v[202:205], v[72:75]
	v_mfma_f32_16x16x32_bf16 v[126:129], v[144:147], v[176:179], v[126:129]
	v_mfma_f32_16x16x32_bf16 v[122:125], v[152:155], v[176:179], v[122:125]
	v_mfma_f32_16x16x32_bf16 v[110:113], v[144:147], v[190:193], v[110:113]
	v_mfma_f32_16x16x32_bf16 v[106:109], v[152:155], v[190:193], v[106:109]
	v_mfma_f32_16x16x32_bf16 v[92:95], v[144:147], v[198:201], v[92:95]
	v_mfma_f32_16x16x32_bf16 v[88:91], v[152:155], v[198:201], v[88:91]
	v_mfma_f32_16x16x32_bf16 v[76:79], v[144:147], v[206:209], v[76:79]
	v_mfma_f32_16x16x32_bf16 v[72:75], v[152:155], v[206:209], v[72:75]
	v_mfma_f32_16x16x32_bf16 v[118:121], v[156:159], v[172:175], v[118:121]
	v_mfma_f32_16x16x32_bf16 v[114:117], v[164:167], v[172:175], v[114:117]
	v_mfma_f32_16x16x32_bf16 v[102:105], v[156:159], v[180:183], v[102:105]
	v_mfma_f32_16x16x32_bf16 v[98:101], v[164:167], v[180:183], v[98:101]
	v_mfma_f32_16x16x32_bf16 v[84:87], v[156:159], v[194:197], v[84:87]
	v_mfma_f32_16x16x32_bf16 v[80:83], v[164:167], v[194:197], v[80:83]
	v_mfma_f32_16x16x32_bf16 v[68:71], v[156:159], v[202:205], v[68:71]
	v_mfma_f32_16x16x32_bf16 v[64:67], v[164:167], v[202:205], v[64:67]
	v_mfma_f32_16x16x32_bf16 v[118:121], v[160:163], v[176:179], v[118:121]
	v_mfma_f32_16x16x32_bf16 v[114:117], v[168:171], v[176:179], v[114:117]
	v_mfma_f32_16x16x32_bf16 v[102:105], v[160:163], v[190:193], v[102:105]
	v_mfma_f32_16x16x32_bf16 v[98:101], v[168:171], v[190:193], v[98:101]
	v_mfma_f32_16x16x32_bf16 v[84:87], v[160:163], v[198:201], v[84:87]
	v_mfma_f32_16x16x32_bf16 v[80:83], v[168:171], v[198:201], v[80:83]
	v_mfma_f32_16x16x32_bf16 v[68:71], v[160:163], v[206:209], v[68:71]
	v_mfma_f32_16x16x32_bf16 v[64:67], v[168:171], v[206:209], v[64:67]
	s_setprio 0
	s_barrier
	s_add_i32 s18, s35, s14
	s_mov_b32 m0, s18
	ds_read_b128 v[172:175], v143 offset:49152
	ds_read_b128 v[176:179], v143 offset:50176
	ds_read_b128 v[180:183], v143 offset:51200
	ds_read_b128 v[190:193], v143 offset:52224
	ds_read_b128 v[194:197], v143 offset:53248
	ds_read_b128 v[198:201], v143 offset:54272
	ds_read_b128 v[202:205], v143 offset:55296
	ds_read_b128 v[206:209], v143 offset:56320
	global_load_lds_dwordx4 v96, s[62:63]
	s_add_i32 m0, s18, 0x2000
	s_add_u32 s18, s62, 0xb0000
	s_addc_u32 s19, s63, 0
	s_add_i32 s35, s44, s14
	global_load_lds_dwordx4 v134, s[62:63]
	s_mov_b32 m0, s35
	s_nop 0
	global_load_lds_dwordx4 v96, s[18:19]
	s_add_i32 m0, s35, 0x2000
	s_nop 0
	global_load_lds_dwordx4 v134, s[18:19]
	s_waitcnt vmcnt(6)
	s_waitcnt lgkmcnt(0)
	s_barrier
	s_setprio 1
	s_waitcnt lgkmcnt(0)
	v_mfma_f32_16x16x32_bf16 v[60:63], v[136:139], v[172:175], v[60:63]
	v_mfma_f32_16x16x32_bf16 v[56:59], v[148:151], v[172:175], v[56:59]
	v_mfma_f32_16x16x32_bf16 v[44:47], v[136:139], v[180:183], v[44:47]
	v_mfma_f32_16x16x32_bf16 v[40:43], v[148:151], v[180:183], v[40:43]
	v_mfma_f32_16x16x32_bf16 v[28:31], v[136:139], v[194:197], v[28:31]
	v_mfma_f32_16x16x32_bf16 v[24:27], v[148:151], v[194:197], v[24:27]
	v_mfma_f32_16x16x32_bf16 v[12:15], v[136:139], v[202:205], v[12:15]
	v_mfma_f32_16x16x32_bf16 v[8:11], v[148:151], v[202:205], v[8:11]
	v_mfma_f32_16x16x32_bf16 v[60:63], v[144:147], v[176:179], v[60:63]
	v_mfma_f32_16x16x32_bf16 v[56:59], v[152:155], v[176:179], v[56:59]
	v_mfma_f32_16x16x32_bf16 v[44:47], v[144:147], v[190:193], v[44:47]
	v_mfma_f32_16x16x32_bf16 v[40:43], v[152:155], v[190:193], v[40:43]
	v_mfma_f32_16x16x32_bf16 v[28:31], v[144:147], v[198:201], v[28:31]
	v_mfma_f32_16x16x32_bf16 v[24:27], v[152:155], v[198:201], v[24:27]
	v_mfma_f32_16x16x32_bf16 v[12:15], v[144:147], v[206:209], v[12:15]
	v_mfma_f32_16x16x32_bf16 v[8:11], v[152:155], v[206:209], v[8:11]
	v_mfma_f32_16x16x32_bf16 v[52:55], v[156:159], v[172:175], v[52:55]
	v_mfma_f32_16x16x32_bf16 v[48:51], v[164:167], v[172:175], v[48:51]
	v_mfma_f32_16x16x32_bf16 v[36:39], v[156:159], v[180:183], v[36:39]
	v_mfma_f32_16x16x32_bf16 v[32:35], v[164:167], v[180:183], v[32:35]
	v_mfma_f32_16x16x32_bf16 v[20:23], v[156:159], v[194:197], v[20:23]
	v_mfma_f32_16x16x32_bf16 v[16:19], v[164:167], v[194:197], v[16:19]
	v_mfma_f32_16x16x32_bf16 v[4:7], v[156:159], v[202:205], v[4:7]
	v_mfma_f32_16x16x32_bf16 v[0:3], v[164:167], v[202:205], v[0:3]
	v_mfma_f32_16x16x32_bf16 v[52:55], v[160:163], v[176:179], v[52:55]
	v_mfma_f32_16x16x32_bf16 v[48:51], v[168:171], v[176:179], v[48:51]
	v_mfma_f32_16x16x32_bf16 v[36:39], v[160:163], v[190:193], v[36:39]
	v_mfma_f32_16x16x32_bf16 v[32:35], v[168:171], v[190:193], v[32:35]
	v_mfma_f32_16x16x32_bf16 v[20:23], v[160:163], v[198:201], v[20:23]
	v_mfma_f32_16x16x32_bf16 v[16:19], v[168:171], v[198:201], v[16:19]
	v_mfma_f32_16x16x32_bf16 v[4:7], v[160:163], v[206:209], v[4:7]
	v_mfma_f32_16x16x32_bf16 v[0:3], v[168:171], v[206:209], v[0:3]
	s_setprio 0
	s_barrier
	s_add_i32 s85, s85, 2
	s_add_u32 s81, s81, 0x100
	s_addc_u32 s82, s82, 0
	s_add_u32 s83, s83, 0x100
	s_addc_u32 s84, s84, 0
	s_add_u32 s60, s60, 0x100
	s_addc_u32 s61, s61, 0
	s_cmp_gt_u32 s85, 41
	s_cbranch_scc0 .LBB0_703
	s_and_b64 vcc, exec, s[30:31]
	s_cbranch_vccz .LBB0_706
	s_barrier
